# sample-attention loop with one workgroup barrier per tile: exp segment of the previous tile at the top of the iteration, P.V lags two tiles, four bf16 tile buffers, double-buffered probability and nor
# speedup vs baseline: 1.0037x; 1.0037x over previous
; #define LAS __attribute__((address_space(3)))
; DI void attn_sample_phase(const Args& a, LAS unsigned char* lds, int vcu, int G, int tid, int lane, int wave) {
;     ...
;             const int c3n = (c3 == 2) ? 0 : c3 + 1, c3p = (c3 == 0) ? 2 : c3 - 1;
;             if (j > 0) SA_PV(c3p);
;             { const LAS unsigned char* c8b = C8 + (j & 1) * 8704; const LAS float* spe = SSPE + (j & 1) * 32;
; #pragma unroll
;                 for (int kb = 0; kb < 2; ++kb) { f32x4 acc[4] = {};
; #pragma unroll
;                     for (int ks = 0; ks < 2; ++ks) { const LAS unsigned char* ap = c8b + (kb * 16 + r16) * 272 + 128 * ks + 32 * q4;
;                         const u32x4 x0 = *(const LAS u32x4*)ap, x1 = *(const LAS u32x4*)(ap + 16);
;                         const v8i_t af = {(int)x0.x, (int)x0.y, (int)x0.z, (int)x0.w, (int)x1.x, (int)x1.y, (int)x1.z, (int)x1.w};
; #pragma unroll
;                         for (int nb = 0; nb < 4; ++nb) acc[nb] = __builtin_amdgcn_mfma_scale_f32_16x16x128_f8f6f4(af, wf8[nb][ks], acc[nb], 0, 0, 0, 0x7F7F7F7F, 0, 0x7F7F7F7F); }
;                     f32x4 sq = (acc[0] * acc[0] + acc[1] * acc[1] + acc[2] * acc[2] + acc[3] * acc[3]) * (1.f / 256.f);
;                     sq.x = row16_sum(sq.x); sq.y = row16_sum(sq.y); sq.z = row16_sum(sq.z); sq.w = row16_sum(sq.w);
;                     if (r16 == 0) { const f32x4 pe = *(const LAS f32x4*)(spe + kb * 16 + 4 * q4); f32x4 r;
;                         r.x = __builtin_amdgcn_rsqf((sq.x + pe.x) * (1.f / 96.f) + EPS); r.y = __builtin_amdgcn_rsqf((sq.y + pe.y) * (1.f / 96.f) + EPS);
;                         r.z = __builtin_amdgcn_rsqf((sq.z + pe.z) * (1.f / 96.f) + EPS); r.w = __builtin_amdgcn_rsqf((sq.w + pe.w) * (1.f / 96.f) + EPS);
;                         *(LAS f32x4*)(RI + wave * 32 + kb * 16 + 4 * q4) = r; } } }
;     ...
;             if (wave < 4) { const int kb = wave >> 1, nb2 = wave & 1; const int row = nb2 * 16 + r16, hrow = row >> 2; const f32x4 ri = *(const LAS f32x4*)(RI + hrow * 32 + kb * 16 + 4 * q4);
;                 const float p0 = __builtin_amdgcn_exp2f(sa.x * ri.x - cB), p1 = __builtin_amdgcn_exp2f(sa.y * ri.y - cB), p2 = __builtin_amdgcn_exp2f(sa.z * ri.z - cB), p3 = __builtin_amdgcn_exp2f(sa.w * ri.w - cB);
;                 lsum += (p0 + p1) + (p2 + p3);
;                 u32x2 w; w.x = pk2(p0, p1); w.y = pk2(p2, p3); *(LAS u32x2*)(PT + row * 40 + kb * 16 + 4 * q4) = w; }
.LBB0_902:
	s_mov_b32 s98, s17
	s_add_i32 s26, s25, -2
	s_cmp_lg_u64 s[2:3], 0
	s_cbranch_scc1 .Lsa_a4
	s_cmp_eq_u32 s25, 2
	s_cbranch_scc1 .Lsa_front
	s_and_b32 s8, s26, 1
	s_xor_b32 s8, s8, 1
	s_mul_i32 s8, s8, 0x5a00
	v_add_u32_e32 v212, s8, v198
	ds_read_b128 v[212:215], v212
	s_waitcnt lgkmcnt(0)
	v_fma_f32 v2, v136, v212, -v159
	v_fma_f32 v137, v137, v213, -v159
	v_fma_f32 v212, v138, v214, -v159
	v_exp_f32_e32 v136, v2
	v_fma_f32 v2, v139, v215, -v159
	v_exp_f32_e32 v138, v137
	v_exp_f32_e32 v137, v212
	v_exp_f32_e32 v139, v2
	s_nop 0
	v_pk_add_f32 v[212:213], v[136:137], v[138:139]
	s_nop 0
	v_add_f32_e32 v2, v212, v213
	v_cvt_pk_bf16_f32 v136, v136, v138
	v_add_f32_e32 v211, v211, v2
	v_cvt_pk_bf16_f32 v137, v137, v139
	v_add_u32_e32 v2, s8, v199
	ds_write_b64 v2, v[136:137]
.Lsa_front:
.LBB0_904:
	s_and_b32 s8, s26, 1
	s_mul_i32 s19, s8, 0x5a00
	s_mul_i32 s9, s8, 0x2200
	v_add_u32_e32 v2, s9, v202
	s_lshl_b32 s8, s8, 7
	s_add_i32 s8, s8, 0x400
	s_sub_i32 s8, s8, s99
	v_add_u32_e32 v254, s8, v255
	ds_read_b128 v[212:215], v2 offset:56832
	ds_read_b128 v[216:219], v2 offset:56848
	ds_read_b128 v[236:239], v2 offset:56960
	ds_read_b128 v[240:243], v2 offset:56976
	ds_read_b128 v[246:249], v2 offset:61184
	ds_read_b128 v[250:253], v2 offset:61200
	ds_read_b32 v232, v254
	s_waitcnt lgkmcnt(5)
	v_mfma_f32_16x16x128_f8f6f4 v[220:223], v[36:43], v[212:219], 0
	v_mfma_f32_16x16x128_f8f6f4 v[136:139], v[20:27], v[212:219], 0
	v_mfma_f32_16x16x128_f8f6f4 v[224:227], v[52:59], v[212:219], 0
	v_mfma_f32_16x16x128_f8f6f4 v[228:231], v[68:75], v[212:219], 0
	s_waitcnt lgkmcnt(3)
	v_mfma_f32_16x16x128_f8f6f4 v[220:223], v[44:51], v[236:243], v[220:223]
	ds_read_b128 v[212:215], v2 offset:61312
	ds_read_b128 v[216:219], v2 offset:61328
	v_mfma_f32_16x16x128_f8f6f4 v[136:139], v[28:35], v[236:243], v[136:139]
	v_mfma_f32_16x16x128_f8f6f4 v[224:227], v[60:67], v[236:243], v[224:227]
	v_mfma_f32_16x16x128_f8f6f4 v[228:231], v[76:83], v[236:243], v[228:231]
	s_add_i32 s9, s98, 2
	s_and_b32 s9, s9, 3
	s_cmp_eq_u32 s9, 3
	s_mul_i32 s9, s9, 0x2500
	s_cselect_b32 s9, 0xbe00, s9
	v_lshl_add_u32 v2, s9, 1, v201
	s_nop 0
	v_mul_f32_e32 v234, v220, v220
	v_fmac_f32_e32 v234, v221, v221
	v_fmac_f32_e32 v234, v222, v222
	v_fmac_f32_e32 v234, v223, v223
	s_waitcnt lgkmcnt(3)
	v_mfma_f32_16x16x128_f8f6f4 v[220:223], v[36:43], v[246:253], 0
	v_fmac_f32_e32 v234, v136, v136
	v_fmac_f32_e32 v234, v137, v137
	v_fmac_f32_e32 v234, v138, v138
	v_fmac_f32_e32 v234, v139, v139
	v_mfma_f32_16x16x128_f8f6f4 v[136:139], v[68:75], v[246:253], 0
	v_fmac_f32_e32 v234, v224, v224
	v_fmac_f32_e32 v234, v225, v225
	v_fmac_f32_e32 v234, v226, v226
	v_fmac_f32_e32 v234, v227, v227
	v_mfma_f32_16x16x128_f8f6f4 v[224:227], v[20:27], v[246:253], 0
	v_fmac_f32_e32 v234, v228, v228
	v_fmac_f32_e32 v234, v229, v229
	v_fmac_f32_e32 v234, v230, v230
	v_fmac_f32_e32 v234, v231, v231
	v_mfma_f32_16x16x128_f8f6f4 v[228:231], v[52:59], v[246:253], 0
	s_waitcnt lgkmcnt(0)
	v_mfma_f32_16x16x128_f8f6f4 v[220:223], v[44:51], v[212:219], v[220:223]
	s_cmp_lt_u32 s25, 4
	s_cbranch_scc1 .Lsa_nopvA
	ds_read_b64_tr_b16 v[236:237], v2
	ds_read_b64_tr_b16 v[238:239], v2 offset:2368
	v_add_u32_e32 v233, s19, v196
	ds_read_b128 v[246:249], v233
	ds_read_b128 v[250:253], v233 offset:32
	ds_read_b64_tr_b16 v[240:241], v2 offset:9472
	ds_read_b64_tr_b16 v[242:243], v2 offset:11840

; #define LAS __attribute__((address_space(3)))
; #define MFMA16(a, b, c) __builtin_amdgcn_mfma_f32_16x16x32_bf16((a), (b), (c), 0, 0, 0)
; DI void attn_sample_phase(const Args& a, LAS unsigned char* lds, int vcu, int G, int tid, int lane, int wave) {
;     ...
;                     f32x4 sq = (acc[0] * acc[0] + acc[1] * acc[1] + acc[2] * acc[2] + acc[3] * acc[3]) * (1.f / 256.f);
;                     sq.x = row16_sum(sq.x); sq.y = row16_sum(sq.y); sq.z = row16_sum(sq.z); sq.w = row16_sum(sq.w);
;                     if (r16 == 0) { const f32x4 pe = *(const LAS f32x4*)(spe + kb * 16 + 4 * q4); f32x4 r;
;                         r.x = __builtin_amdgcn_rsqf((sq.x + pe.x) * (1.f / 96.f) + EPS); r.y = __builtin_amdgcn_rsqf((sq.y + pe.y) * (1.f / 96.f) + EPS);
;                         r.z = __builtin_amdgcn_rsqf((sq.z + pe.z) * (1.f / 96.f) + EPS); r.w = __builtin_amdgcn_rsqf((sq.w + pe.w) * (1.f / 96.f) + EPS);
;                         *(LAS f32x4*)(RI + wave * 32 + kb * 16 + 4 * q4) = r; } } }
;             f32x4 sa = {0.f, 0.f, 0.f, 0.f};
;             if (wave < 4) { const int kb = wave >> 1, nb2 = wave & 1; const LAS bf16* cb = Cs + c3 * (32 * CSW);
; #pragma unroll
;                 for (int s9 = 0; s9 < 9; ++s9) { const bf16x8 af = *(const LAS bf16x8*)(cb + (kb * 16 + r16) * CSW + 32 * s9 + 8 * q4);
;                     sa = MFMA16(af, qfr[s9], sa); } (void)nb2; }
.Lsa_pvdone:
	v_mul_f32_e32 v235, v220, v220
	v_fmac_f32_e32 v235, v221, v221
	v_fmac_f32_e32 v235, v222, v222
	v_fmac_f32_e32 v235, v223, v223
	v_fmac_f32_e32 v235, v136, v136
	v_fmac_f32_e32 v235, v137, v137
	v_fmac_f32_e32 v235, v138, v138
	v_fmac_f32_e32 v235, v139, v139
	v_fmac_f32_e32 v235, v224, v224
	v_fmac_f32_e32 v235, v225, v225
	v_fmac_f32_e32 v235, v226, v226
	v_fmac_f32_e32 v235, v227, v227
	v_fmac_f32_e32 v235, v228, v228
	v_fmac_f32_e32 v235, v229, v229
	v_fmac_f32_e32 v235, v230, v230
	v_fmac_f32_e32 v235, v231, v231
	s_nop 1
	v_permlane32_swap_b32_e32 v234, v235
	v_add_f32_e32 v234, v234, v235
	v_mov_b32_e32 v233, v234
	s_nop 1
	v_permlane16_swap_b32_e32 v233, v234
	v_add_f32_e32 v234, v234, v233
	v_fmamk_f32 v234, v234, 0x3b800000, v232
	v_fmamk_f32 v234, v234, 0x3c2aaaab, v209
	v_rsq_f32_e32 v234, v234
	v_add_u32_e32 v233, s19, v255
	ds_write_b32 v233, v234
.LBB0_908:
	s_andn2_b64 s[8:9], exec, s[10:11]
	s_andn2_b64 vcc, exec, s[10:11]
	s_cbranch_vccnz .LBB0_910
	s_cmp_eq_u32 s98, 3
	s_mul_i32 s18, s98, 0x4a00
	s_cselect_b32 s18, 0x17c00, s18
	v_add_u32_e32 v2, s18, v197
	ds_read_b128 v[136:139], v2
	ds_read_b128 v[212:215], v2 offset:64
	ds_read_b128 v[216:219], v2 offset:128
	s_waitcnt lgkmcnt(2)
	v_mfma_f32_16x16x32_bf16 v[136:139], v[136:139], v[84:87], 0
	s_waitcnt lgkmcnt(1)
	v_mfma_f32_16x16x32_bf16 v[136:139], v[212:215], v[88:91], v[136:139]
	ds_read_b128 v[212:215], v2 offset:192
	s_waitcnt lgkmcnt(1)
	v_mfma_f32_16x16x32_bf16 v[136:139], v[216:219], v[92:95], v[136:139]
	ds_read_b128 v[216:219], v2 offset:256
	s_waitcnt lgkmcnt(1)
	v_mfma_f32_16x16x32_bf16 v[136:139], v[212:215], v[96:99], v[136:139]
	ds_read_b128 v[212:215], v2 offset:320
	s_waitcnt lgkmcnt(1)
	v_mfma_f32_16x16x32_bf16 v[136:139], v[216:219], v[100:103], v[136:139]
	ds_read_b128 v[216:219], v2 offset:384
	s_waitcnt lgkmcnt(1)
	v_mfma_f32_16x16x32_bf16 v[136:139], v[212:215], v[104:107], v[136:139]
	ds_read_b128 v[212:215], v2 offset:448
	s_waitcnt lgkmcnt(1)
	v_mfma_f32_16x16x32_bf16 v[136:139], v[216:219], v[108:111], v[136:139]
	s_waitcnt lgkmcnt(0)
	v_mfma_f32_16x16x32_bf16 v[136:139], v[212:215], v[112:115], v[136:139]
	ds_read_b128 v[212:215], v2 offset:512
	s_waitcnt lgkmcnt(0)
	v_mfma_f32_16x16x32_bf16 v[136:139], v[212:215], v[116:119], v[136:139]

; DI void attn_sample_phase(const Args& a, LAS unsigned char* lds, int vcu, int G, int tid, int lane, int wave) {
;     ...
;             const int c3n = (c3 == 2) ? 0 : c3 + 1, c3p = (c3 == 0) ? 2 : c3 - 1;
.Lsa_a4:
	s_add_i32 s17, s17, 1
	s_and_b32 s17, s17, 3
	s_cmpk_eq_i32 s25, 0x81
	s_cbranch_scc1 .Lsa_a4end
	s_add_i32 s18, s25, -1
	s_and_b32 s28, s18, 1
	s_cmp_eq_u32 s17, 3
	s_mul_i32 s27, s17, 0x4a00
	s_cselect_b32 s27, 0x17c00, s27
	s_mul_i32 s18, s28, 0x2200
	v_add3_u32 v216, s18, v184, v180
	v_lshl_add_u32 v217, v181, 1, v182
	v_add_u32_e32 v217, s27, v217
	s_waitcnt vmcnt(3)
	v_cvt_pk_fp8_f32 v212, v120, v121
	v_cvt_pk_bf16_f32 v214, v120, v121
	v_cvt_pk_fp8_f32 v212, v122, v123 op_sel:[0,0,1]
	v_cvt_pk_bf16_f32 v215, v122, v123
	ds_write_b64 v217, v[214:215]
	ds_write_b32 v216, v212 offset:56832
	s_waitcnt vmcnt(2)
	v_cvt_pk_fp8_f32 v213, v124, v125
	v_cvt_pk_bf16_f32 v218, v124, v125
	v_cvt_pk_fp8_f32 v213, v126, v127 op_sel:[0,0,1]
	v_cvt_pk_bf16_f32 v219, v126, v127
	ds_write_b64 v217, v[218:219] offset:4736
	ds_write_b32 v216, v213 offset:59008
	s_waitcnt vmcnt(1)
	v_cvt_pk_fp8_f32 v212, v128, v129
	v_cvt_pk_bf16_f32 v214, v128, v129
	v_cvt_pk_fp8_f32 v212, v130, v131 op_sel:[0,0,1]
	v_cvt_pk_bf16_f32 v215, v130, v131
	ds_write_b64 v217, v[214:215] offset:9472
	ds_write_b32 v216, v212 offset:61184
	s_waitcnt vmcnt(0)
	v_cvt_pk_fp8_f32 v213, v132, v133
	v_cvt_pk_bf16_f32 v218, v132, v133
	v_cvt_pk_fp8_f32 v213, v134, v135 op_sel:[0,0,1]
	v_cvt_pk_bf16_f32 v219, v134, v135
	ds_write_b64 v217, v[218:219] offset:14208
	ds_write_b32 v216, v213 offset:63360
	s_and_saveexec_b64 s[18:19], s[2:3]
	s_cbranch_execz .LBB0_915
	v_pk_mul_f32 v[212:213], v[172:173], v[172:173]
	v_pk_mul_f32 v[214:215], v[174:175], v[174:175]
	v_add_f32_e32 v212, v212, v213
	v_add_f32_e32 v2, v214, v215
	v_add_f32_e32 v2, v212, v2
	v_mov_b32_e32 v212, 0
	s_nop 0
	v_add_f32_dpp v2, v2, v2 quad_perm:[1,0,3,2] row_mask:0xf bank_mask:0xf bound_ctrl:1
	s_nop 1
	v_add_f32_dpp v2, v2, v2 quad_perm:[2,3,0,1] row_mask:0xf bank_mask:0xf bound_ctrl:1
	s_nop 1
	v_mov_b32_dpp v212, v2 row_half_mirror row_mask:0xf bank_mask:0xf
	s_and_saveexec_b64 s[20:21], s[4:5]
	v_add_f32_e32 v2, v2, v212
	v_lshl_add_u32 v212, s28, 7, v191
	ds_write_b32 v212, v2
	s_or_b64 exec, exec, s[20:21]
	v_pk_mul_f32 v[214:215], v[146:147], v[174:175]
	v_pk_mul_f32 v[212:213], v[144:145], v[172:173]
	v_pk_mul_f32 v[216:217], v[214:215], v[178:179]
	s_nop 0
	v_pk_fma_f32 v[216:217], v[212:213], v[176:177], v[216:217] neg_lo:[0,0,1] neg_hi:[0,0,1]
	v_pk_mul_f32 v[212:213], v[212:213], v[178:179]
	v_cvt_pk_bf16_f32 v2, v216, v217
	v_pk_fma_f32 v[212:213], v[176:177], v[214:215], v[212:213]
	v_add3_u32 v214, s27, v192, v1
	v_cvt_pk_bf16_f32 v212, v212, v213
	ds_write2_b32 v214, v2, v212 offset0:128 offset1:136
	v_pk_mul_f32 v[212:213], v[150:151], v[178:179]
	v_pk_mul_f32 v[178:179], v[148:149], v[178:179]
	v_pk_fma_f32 v[212:213], v[148:149], v[176:177], v[212:213] neg_lo:[0,0,1] neg_hi:[0,0,1]
	v_pk_fma_f32 v[178:179], v[150:151], v[176:177], v[178:179]
	v_mov_b64_e32 v[176:177], v[212:213]

; #define LAS __attribute__((address_space(3)))
; DI unsigned pk2(float lo, float hi) { f32x2 v = {lo, hi}; bf16x2_t b = __builtin_convertvector(v, bf16x2_t); return __builtin_bit_cast(unsigned, b); }
; DI void attn_sample_phase(const Args& a, LAS unsigned char* lds, int vcu, int G, int tid, int lane, int wave) {
;     ...
;             __syncthreads();
;             if (wave < 4) { const int kb = wave >> 1, nb2 = wave & 1; const int row = nb2 * 16 + r16, hrow = row >> 2; const f32x4 ri = *(const LAS f32x4*)(RI + hrow * 32 + kb * 16 + 4 * q4);
;                 const float p0 = __builtin_amdgcn_exp2f(sa.x * ri.x - cB), p1 = __builtin_amdgcn_exp2f(sa.y * ri.y - cB), p2 = __builtin_amdgcn_exp2f(sa.z * ri.z - cB), p3 = __builtin_amdgcn_exp2f(sa.w * ri.w - cB);
;                 lsum += (p0 + p1) + (p2 + p3);
;                 u32x2 w; w.x = pk2(p0, p1); w.y = pk2(p2, p3); *(LAS u32x2*)(PT + row * 40 + kb * 16 + 4 * q4) = w; }
;             __syncthreads();
;             c3 = c3n;
;         }
;         SA_PV(((c3 == 0) ? 2 : c3 - 1));
;         lsum += __shfl_xor(lsum, 16); lsum += __shfl_xor(lsum, 32);
;         if (wave < 4 && q4 == 0) (void)__hip_atomic_fetch_add(LRED + (wave & 1) * 16 + r16, lsum, __ATOMIC_RELAXED, __HIP_MEMORY_SCOPE_WORKGROUP);
.Lsa_a4end:
	s_cmp_lg_u64 s[2:3], 0
	s_cbranch_scc1 .Lsa_front
.LBB0_919:
	s_branch .LBB0_901
.LBB0_921:
	s_cmp_lg_u64 s[2:3], 0
	s_cbranch_scc1 .Lsa_drain1
	s_movk_i32 s8, 0x5a00
	v_add_u32_e32 v212, s8, v198
	ds_read_b128 v[212:215], v212
	s_waitcnt lgkmcnt(0)
	v_fma_f32 v2, v136, v212, -v159
	v_fma_f32 v137, v137, v213, -v159
	v_fma_f32 v212, v138, v214, -v159
	v_exp_f32_e32 v136, v2
	v_fma_f32 v2, v139, v215, -v159
	v_exp_f32_e32 v138, v137
	v_exp_f32_e32 v137, v212
	v_exp_f32_e32 v139, v2
	s_nop 0
	v_pk_add_f32 v[212:213], v[136:137], v[138:139]
	s_nop 0
	v_add_f32_e32 v2, v212, v213
	v_cvt_pk_bf16_f32 v136, v136, v138
	v_add_f32_e32 v211, v211, v2
	v_cvt_pk_bf16_f32 v137, v137, v139
	v_add_u32_e32 v2, s8, v199
	ds_write_b64 v2, v[136:137]
.Lsa_drain1:
	s_waitcnt lgkmcnt(0)
	s_barrier
	s_mov_b32 s8, 0x4a00
	v_lshl_add_u32 v2, s8, 1, v201
	v_mov_b32_e32 v100, v196
	ds_read_b64_tr_b16 v[84:85], v2
	ds_read_b64_tr_b16 v[86:87], v2 offset:2368
	ds_read_b128 v[88:91], v100
	ds_read_b128 v[92:95], v100 offset:32
	ds_read_b64_tr_b16 v[96:97], v2 offset:9472
	ds_read_b64_tr_b16 v[98:99], v2 offset:11840
	s_waitcnt lgkmcnt(3)
	v_mfma_f32_32x32x16_bf16 v[4:19], v[84:87], v[88:91], v[4:19]
	s_waitcnt lgkmcnt(0)
	v_mfma_f32_32x32x16_bf16 v[4:19], v[96:99], v[92:95], v[4:19]
	s_mov_b32 s8, 0xbe00
	v_lshl_add_u32 v2, s8, 1, v201
	v_add_u32_e32 v100, 0x5a00, v196
	ds_read_b64_tr_b16 v[84:85], v2
	ds_read_b64_tr_b16 v[86:87], v2 offset:2368
	ds_read_b128 v[88:91], v100
	ds_read_b128 v[92:95], v100 offset:32
	ds_read_b64_tr_b16 v[96:97], v2 offset:9472
	ds_read_b64_tr_b16 v[98:99], v2 offset:11840
	s_waitcnt lgkmcnt(3)
	v_mfma_f32_32x32x16_bf16 v[4:19], v[84:87], v[88:91], v[4:19]
	s_waitcnt lgkmcnt(0)
	v_mfma_f32_32x32x16_bf16 v[4:19], v[96:99], v[92:95], v[4:19]
	ds_bpermute_b32 v2, v141, v211
	s_waitcnt lgkmcnt(0)
	v_add_f32_e32 v2, v211, v2
	ds_bpermute_b32 v84, v143, v2
	s_and_saveexec_b64 s[8:9], s[12:13]
	s_cbranch_execz .LBB0_923
	s_waitcnt lgkmcnt(0)
	v_add_f32_e32 v2, v2, v84
	ds_add_f32 v200, v2
